# attention O hand-off rows moved as 16-byte pieces (permlane16 swizzle) instead of 8-byte pieces
# speedup vs baseline: 1.0176x; 1.0176x over previous
.LBB0_174:
	v_writelane_b32 v248, s10, 5
	v_writelane_b32 v248, s16, 3
	s_nop 1
	v_writelane_b32 v248, s17, 4
	s_or_b64 exec, exec, s[4:5]
	v_readlane_b32 s4, v249, 15
	v_readlane_b32 s5, v249, 16
	s_andn2_b64 vcc, exec, s[4:5]
	s_cbranch_vccnz .LBB0_203
	s_waitcnt lgkmcnt(0)
	s_barrier
	v_readfirstlane_b32 s67, v158
	s_lshr_b32 s67, s67, 6
	s_lshr_b32 s68, s67, 2
	v_and_b32_e32 v0, 63, v158
	v_and_b32_e32 v1, 15, v0
	v_lshrrev_b32_e32 v2, 4, v0
	s_lshl_b32 s4, s67, 4
	v_add_u32_e32 v17, s4, v1
	v_and_b32_e32 v37, 6, v1
	v_xor_b32_e32 v37, v2, v37
	v_lshlrev_b32_e32 v37, 4, v37
	v_lshl_add_u32 v4, v1, 7, v37
	v_xor_b32_e32 v5, 64, v4
	v_lshrrev_b32_e32 v38, 2, v1
	v_lshl_add_u32 v38, v2, 2, v38
	v_add_u32_e32 v39, s4, v38
	v_and_b32_e32 v40, 6, v38
	v_and_b32_e32 v41, 3, v1
	v_lshrrev_b32_e32 v42, 1, v41
	v_and_b32_e32 v43, 1, v1
	v_lshlrev_b32_e32 v43, 3, v43
	v_add_u32_e32 v45, 0x90, v39
	v_and_b32_e32 v45, 0xff, v45
	v_or_b32_e32 v44, 0, v42
	v_xor_b32_e32 v44, v44, v40
	v_lshlrev_b32_e32 v44, 4, v44
	v_add_u32_e32 v44, v44, v43
	v_lshl_add_u32 v46, v38, 7, v44
	v_add_u32_e32 v6, 0x10000, v46
	v_or_b32_e32 v44, 2, v42
	v_xor_b32_e32 v44, v44, v40
	v_lshlrev_b32_e32 v44, 4, v44
	v_add_u32_e32 v44, v44, v43
	v_lshl_add_u32 v46, v38, 7, v44
	v_add_u32_e32 v7, 0x10000, v46
	v_or_b32_e32 v44, 4, v42
	v_xor_b32_e32 v44, v44, v40
	v_lshlrev_b32_e32 v44, 4, v44
	v_add_u32_e32 v44, v44, v43
	v_lshl_add_u32 v46, v38, 7, v44
	v_add_u32_e32 v8, 0x10000, v46
	v_or_b32_e32 v44, 6, v42
	v_xor_b32_e32 v44, v44, v40
	v_lshlrev_b32_e32 v44, 4, v44
	v_add_u32_e32 v44, v44, v43
	v_lshl_add_u32 v46, v38, 7, v44
	v_add_u32_e32 v9, 0x10000, v46
	v_lshrrev_b32_e32 v14, 3, v158
	v_and_b32_e32 v44, 7, v0
	v_lshrrev_b32_e32 v45, 3, v0
	v_and_b32_e32 v45, 6, v45
	v_xor_b32_e32 v44, v44, v45
	v_lshlrev_b32_e32 v15, 4, v44
	v_lshlrev_b32_e32 v44, 2, v2
	v_sub_u32_e32 v45, v1, v44
	v_add_u32_e32 v45, 0x80, v45
	v_cvt_f32_i32_e32 v16, v45
	v_lshlrev_b32_e32 v18, 4, v2
	v_and_b32_e32 v46, 1, v2
	v_lshlrev_b32_e32 v46, 5, v46
	v_lshrrev_b32_e32 v47, 1, v2
	v_lshl_or_b32 v19, v47, 4, v46
	v_or_b32_e32 v45, 0, v44
	v_cmp_lt_u32_e64 s[54:55], v45, v1
	v_cmp_gt_u32_e64 s[70:71], v45, v1
	v_or_b32_e32 v45, 1, v44
	v_cmp_lt_u32_e64 s[56:57], v45, v1
	v_cmp_gt_u32_e64 s[72:73], v45, v1
	v_or_b32_e32 v45, 2, v44
	v_cmp_lt_u32_e64 s[58:59], v45, v1
	v_cmp_gt_u32_e64 s[74:75], v45, v1
	v_or_b32_e32 v45, 3, v44
	v_cmp_lt_u32_e64 s[60:61], v45, v1
	v_cmp_gt_u32_e64 s[76:77], v45, v1
	v_mov_b32_e32 v190, 0
	v_mov_b32_e32 v191, 0
	s_mov_b32 s63, s2

.Latt_half_3:
	s_add_i32 s7, s5, 128
	s_and_b32 s7, s7, 511
	s_lshl_b32 s7, s7, 7
	s_add_i32 m0, s7, s9
	s_add_i32 s7, s6, 128
	v_add_u32_e32 v0, s7, v14
	v_lshlrev_b32_e32 v0, s28, v0
	v_add_u32_e32 v0, s29, v0
	v_max_i32_e32 v0, 0, v0
	v_lshl_or_b32 v2, v0, 7, v15
	v_lshl_add_u64 v[42:43], s[38:39], 0, v[2:3]
	global_load_lds_dwordx4 v[42:43], off nt
	s_add_i32 s7, s5, 192
	s_and_b32 s7, s7, 511
	s_lshl_b32 s7, s7, 7
	s_add_i32 m0, s7, s9
	s_add_i32 s7, s6, 192
	v_add_u32_e32 v0, s7, v14
	v_lshlrev_b32_e32 v0, s28, v0
	v_add_u32_e32 v0, s29, v0
	v_max_i32_e32 v0, 0, v0
	v_lshl_or_b32 v2, v0, 7, v15
	v_lshl_add_u64 v[44:45], s[38:39], 0, v[2:3]
	global_load_lds_dwordx4 v[44:45], off nt
	s_lshl_b32 s5, s30, 7
	v_add_u32_e32 v82, s5, v17
	v_lshlrev_b32_e32 v82, s28, v82
	v_add_u32_e32 v82, s29, v82
	v_lshl_add_u32 v1, v82, 11, v18
	global_load_dwordx4 v[48:51], v1, s[40:41]
	global_load_dwordx4 v[52:55], v1, s[40:41] offset:64
	s_cmp_lt_u32 s4, 16
	s_cbranch_scc1 .Latt_odummy_4
	v_lshl_add_u32 v1, v82, 11, v19
	global_load_dwordx4 v[64:67], v1, s[42:43] offset:0
	global_load_dwordx4 v[68:71], v1, s[42:43] offset:64
	v_lshlrev_b32_e32 v0, 2, v82
	global_load_dword v80, v0, s[44:45]
	s_branch .Latt_odone_5
.Latt_odummy_4:
	global_load_dword v64, v3, s[44:45]
	global_load_dword v68, v3, s[44:45]
	global_load_dword v80, v3, s[44:45]
.Latt_odone_5:
	s_mov_b32 s4, 1
	s_lshr_b32 s11, s4, 4
	s_and_b32 s12, s4, 15
	s_lshl_b32 s28, s11, 1
	s_lshl_b32 s13, s64, 4
	s_add_i32 s13, s13, s12
	s_lshr_b32 s14, s12, 2
	s_and_b32 s15, s12, 3
	s_lshl_b32 s16, s64, 2
	s_add_i32 s15, s16, s15
	s_cmp_eq_u32 s11, 1
	s_cselect_b32 s29, s14, 0
	s_cselect_b32 s30, s15, s13
	s_cmp_eq_u32 s11, 2
	s_cselect_b32 s29, s12, s29
	s_cselect_b32 s30, s64, s30
	s_lshl_b32 s5, s30, 7
	v_add_u32_e32 v82, s5, v17
	v_lshlrev_b32_e32 v82, s28, v82
	v_add_u32_e32 v82, s29, v82
	v_lshl_add_u32 v1, v82, 11, v18
	global_load_dwordx4 v[56:59], v1, s[40:41]
	global_load_dwordx4 v[60:63], v1, s[40:41] offset:64
	s_cmp_lt_u32 s4, 16
	s_cbranch_scc1 .Latt_odummy_6
	v_lshl_add_u32 v1, v82, 11, v19
	global_load_dwordx4 v[72:75], v1, s[42:43] offset:0
	global_load_dwordx4 v[76:79], v1, s[42:43] offset:64
	v_lshlrev_b32_e32 v0, 2, v82
	global_load_dword v81, v0, s[44:45]
	s_branch .Latt_odone_7
.Latt_odummy_6:
	global_load_dword v72, v3, s[44:45]
	global_load_dword v76, v3, s[44:45]
	global_load_dword v81, v3, s[44:45]

.Latt_n0t_19:
.Latt_n0skip_11:
	s_waitcnt lgkmcnt(10)
	v_mfma_f32_16x16x32_bf16 v[132:135], v[84:87], v[48:51], v[22:25]
	v_mfma_f32_16x16x32_bf16 v[132:135], v[88:91], v[52:55], v[132:135]
	s_waitcnt lgkmcnt(8)
	v_mfma_f32_16x16x32_bf16 v[136:139], v[92:95], v[48:51], v[22:25]
	v_mfma_f32_16x16x32_bf16 v[136:139], v[96:99], v[52:55], v[136:139]
	s_waitcnt lgkmcnt(6)
	v_mfma_f32_16x16x32_bf16 v[140:143], v[100:103], v[48:51], v[22:25]
	v_mfma_f32_16x16x32_bf16 v[140:143], v[104:107], v[52:55], v[140:143]
	s_add_i32 s5, s91, 6
	s_and_b32 s5, s5, 31
	s_lshl_b32 s5, s5, 11
	v_add_u32_e32 v0, s5, v4
	v_add_u32_e32 v1, s5, v5
	ds_read_b128 v[84:87], v0
	ds_read_b128 v[88:91], v1
	s_add_i32 s5, s91, 7
	s_and_b32 s5, s5, 31
	s_lshl_b32 s5, s5, 11
	v_add_u32_e32 v0, s5, v4
	v_add_u32_e32 v1, s5, v5
	ds_read_b128 v[92:95], v0
	ds_read_b128 v[96:99], v1
	s_add_i32 s5, s91, 8
	s_and_b32 s5, s5, 31
	s_lshl_b32 s5, s5, 11
	v_add_u32_e32 v0, s5, v4
	v_add_u32_e32 v1, s5, v5
	ds_read_b128 v[100:103], v0
	ds_read_b128 v[104:107], v1
	s_waitcnt lgkmcnt(10)
	v_mfma_f32_16x16x32_bf16 v[144:147], v[108:111], v[48:51], v[22:25]
	v_mfma_f32_16x16x32_bf16 v[144:147], v[112:115], v[52:55], v[144:147]
	s_waitcnt lgkmcnt(8)
	v_mfma_f32_16x16x32_bf16 v[148:151], v[116:119], v[48:51], v[22:25]
	v_mfma_f32_16x16x32_bf16 v[148:151], v[120:123], v[52:55], v[148:151]
	s_waitcnt lgkmcnt(6)
	v_mfma_f32_16x16x32_bf16 v[152:155], v[124:127], v[48:51], v[22:25]
	v_mfma_f32_16x16x32_bf16 v[152:155], v[128:131], v[52:55], v[152:155]
	s_waitcnt lgkmcnt(4)
	v_mfma_f32_16x16x32_bf16 v[160:163], v[84:87], v[48:51], v[22:25]
	v_mfma_f32_16x16x32_bf16 v[160:163], v[88:91], v[52:55], v[160:163]
	s_waitcnt lgkmcnt(2)
	v_mfma_f32_16x16x32_bf16 v[164:167], v[92:95], v[48:51], v[22:25]
	v_mfma_f32_16x16x32_bf16 v[164:167], v[96:99], v[52:55], v[164:167]
	s_waitcnt lgkmcnt(0)
	v_mfma_f32_16x16x32_bf16 v[168:171], v[100:103], v[48:51], v[22:25]
	v_mfma_f32_16x16x32_bf16 v[168:171], v[104:107], v[52:55], v[168:171]
	s_nop 7
	s_nop 3
	v_cndmask_b32_e64 v132, v132, v223, s[54:55]
	v_cndmask_b32_e64 v133, v133, v223, s[56:57]
	v_cndmask_b32_e64 v134, v134, v223, s[58:59]
	v_cndmask_b32_e64 v135, v135, v223, s[60:61]
	v_cndmask_b32_e64 v168, v168, v223, s[70:71]
	v_cndmask_b32_e64 v169, v169, v223, s[72:73]
	v_cndmask_b32_e64 v170, v170, v223, s[74:75]
	v_cndmask_b32_e64 v171, v171, v223, s[76:77]
	v_max3_f32 v0, v132, v133, v134
	v_max_f32_e32 v0, v0, v135
	v_add_f32_e32 v35, v0, v26
	v_max3_f32 v0, v136, v137, v138
	v_max_f32_e32 v0, v0, v139
	v_add_f32_e32 v0, v0, v27
	v_max_f32_e32 v35, v35, v0
	v_max3_f32 v0, v140, v141, v142
	v_max_f32_e32 v0, v0, v143
	v_add_f32_e32 v0, v0, v28
	v_max_f32_e32 v35, v35, v0
	v_max3_f32 v0, v144, v145, v146
	v_max_f32_e32 v0, v0, v147
	v_add_f32_e32 v0, v0, v29
	v_max_f32_e32 v35, v35, v0
	v_max3_f32 v0, v148, v149, v150
	v_max_f32_e32 v0, v0, v151
	v_add_f32_e32 v0, v0, v30
	v_max_f32_e32 v35, v35, v0
	v_max3_f32 v0, v152, v153, v154
	v_max_f32_e32 v0, v0, v155
	v_add_f32_e32 v0, v0, v31
	v_max_f32_e32 v35, v35, v0
	v_max3_f32 v0, v160, v161, v162
	v_max_f32_e32 v0, v0, v163
	v_add_f32_e32 v0, v0, v32
	v_max_f32_e32 v35, v35, v0
	v_max3_f32 v0, v164, v165, v166
	v_max_f32_e32 v0, v0, v167
	v_add_f32_e32 v0, v0, v33
	v_max_f32_e32 v35, v35, v0
	v_max3_f32 v0, v168, v169, v170
	v_max_f32_e32 v0, v0, v171
	v_add_f32_e32 v0, v0, v34
	v_max_f32_e32 v35, v35, v0
	v_mov_b32_e32 v0, v35
	v_mov_b32_e32 v1, v35
	s_nop 1
	v_permlane16_swap_b32_e32 v0, v1
	s_nop 1
	v_max_f32_e32 v35, v0, v1
	v_mov_b32_e32 v0, v35
	v_mov_b32_e32 v1, v35
	s_nop 1
	v_permlane32_swap_b32_e32 v0, v1
	s_nop 1
	v_max_f32_e32 v35, v0, v1
	v_sub_f32_e32 v2, v26, v35
	v_add_f32_e32 v132, v132, v2
	v_add_f32_e32 v133, v133, v2
	v_add_f32_e32 v134, v134, v2
	v_add_f32_e32 v135, v135, v2
	v_exp_f32_e32 v132, v132
	v_exp_f32_e32 v133, v133
	v_exp_f32_e32 v134, v134
	v_exp_f32_e32 v135, v135
	v_add_f32_e32 v36, 0, v132
	v_add_f32_e32 v36, v133, v36
	v_add_f32_e32 v36, v134, v36
	v_add_f32_e32 v36, v135, v36
	v_cvt_pk_bf16_f32 v172, v132, v133
	v_cvt_pk_bf16_f32 v173, v134, v135
	v_sub_f32_e32 v2, v27, v35
	v_add_f32_e32 v136, v136, v2
	v_add_f32_e32 v137, v137, v2
	v_add_f32_e32 v138, v138, v2
	v_add_f32_e32 v139, v139, v2
	v_exp_f32_e32 v136, v136
	v_exp_f32_e32 v137, v137
	v_exp_f32_e32 v138, v138
	v_exp_f32_e32 v139, v139
	v_add_f32_e32 v36, v136, v36
	v_add_f32_e32 v36, v137, v36
	v_add_f32_e32 v36, v138, v36
	v_add_f32_e32 v36, v139, v36
	v_cvt_pk_bf16_f32 v174, v136, v137
	v_cvt_pk_bf16_f32 v175, v138, v139
	v_sub_f32_e32 v2, v28, v35
	v_add_f32_e32 v140, v140, v2
	v_add_f32_e32 v141, v141, v2
	v_add_f32_e32 v142, v142, v2
	v_add_f32_e32 v143, v143, v2
	v_exp_f32_e32 v140, v140
	v_exp_f32_e32 v141, v141
	v_exp_f32_e32 v142, v142
	v_exp_f32_e32 v143, v143
	v_add_f32_e32 v36, v140, v36
	v_add_f32_e32 v36, v141, v36
	v_add_f32_e32 v36, v142, v36
	v_add_f32_e32 v36, v143, v36
	v_cvt_pk_bf16_f32 v176, v140, v141
	v_cvt_pk_bf16_f32 v177, v142, v143
	v_sub_f32_e32 v2, v29, v35
	v_add_f32_e32 v144, v144, v2
	v_add_f32_e32 v145, v145, v2
	v_add_f32_e32 v146, v146, v2
	v_add_f32_e32 v147, v147, v2
	v_exp_f32_e32 v144, v144
	v_exp_f32_e32 v145, v145
	v_exp_f32_e32 v146, v146
	v_exp_f32_e32 v147, v147
	v_add_f32_e32 v36, v144, v36
	v_add_f32_e32 v36, v145, v36
	v_add_f32_e32 v36, v146, v36
	v_add_f32_e32 v36, v147, v36
	v_cvt_pk_bf16_f32 v178, v144, v145
	v_cvt_pk_bf16_f32 v179, v146, v147
	v_sub_f32_e32 v2, v30, v35
	v_add_f32_e32 v148, v148, v2
	v_add_f32_e32 v149, v149, v2
	v_add_f32_e32 v150, v150, v2
	v_add_f32_e32 v151, v151, v2
	v_exp_f32_e32 v148, v148
	v_exp_f32_e32 v149, v149
	v_exp_f32_e32 v150, v150
	v_exp_f32_e32 v151, v151
	v_add_f32_e32 v36, v148, v36
	v_add_f32_e32 v36, v149, v36
	v_add_f32_e32 v36, v150, v36
	v_add_f32_e32 v36, v151, v36
	v_cvt_pk_bf16_f32 v180, v148, v149
	v_cvt_pk_bf16_f32 v181, v150, v151
	v_sub_f32_e32 v2, v31, v35
	v_add_f32_e32 v152, v152, v2
	v_add_f32_e32 v153, v153, v2
	v_add_f32_e32 v154, v154, v2
	v_add_f32_e32 v155, v155, v2
	v_exp_f32_e32 v152, v152
	v_exp_f32_e32 v153, v153
	v_exp_f32_e32 v154, v154
	v_exp_f32_e32 v155, v155
	v_add_f32_e32 v36, v152, v36
	v_add_f32_e32 v36, v153, v36
	v_add_f32_e32 v36, v154, v36
	v_add_f32_e32 v36, v155, v36
	v_cvt_pk_bf16_f32 v182, v152, v153
	v_cvt_pk_bf16_f32 v183, v154, v155
	v_sub_f32_e32 v2, v32, v35
	v_add_f32_e32 v160, v160, v2
	v_add_f32_e32 v161, v161, v2
	v_add_f32_e32 v162, v162, v2
	v_add_f32_e32 v163, v163, v2
	v_exp_f32_e32 v160, v160
	v_exp_f32_e32 v161, v161
	v_exp_f32_e32 v162, v162
	v_exp_f32_e32 v163, v163
	v_add_f32_e32 v36, v160, v36
	v_add_f32_e32 v36, v161, v36
	v_add_f32_e32 v36, v162, v36
	v_add_f32_e32 v36, v163, v36
	v_cvt_pk_bf16_f32 v184, v160, v161
	v_cvt_pk_bf16_f32 v185, v162, v163
	v_sub_f32_e32 v2, v33, v35
	v_add_f32_e32 v164, v164, v2
	v_add_f32_e32 v165, v165, v2
	v_add_f32_e32 v166, v166, v2
	v_add_f32_e32 v167, v167, v2
	v_exp_f32_e32 v164, v164
	v_exp_f32_e32 v165, v165
	v_exp_f32_e32 v166, v166
	v_exp_f32_e32 v167, v167
	v_add_f32_e32 v36, v164, v36
	v_add_f32_e32 v36, v165, v36
	v_add_f32_e32 v36, v166, v36
	v_add_f32_e32 v36, v167, v36
	v_cvt_pk_bf16_f32 v186, v164, v165
	v_cvt_pk_bf16_f32 v187, v166, v167
	v_sub_f32_e32 v2, v34, v35
	v_add_f32_e32 v168, v168, v2
	v_add_f32_e32 v169, v169, v2
	v_add_f32_e32 v170, v170, v2
	v_add_f32_e32 v171, v171, v2
	v_exp_f32_e32 v168, v168
	v_exp_f32_e32 v169, v169
	v_exp_f32_e32 v170, v170
	v_exp_f32_e32 v171, v171
	v_add_f32_e32 v36, v168, v36
	v_add_f32_e32 v36, v169, v36
	v_add_f32_e32 v36, v170, v36
	v_add_f32_e32 v36, v171, v36
	v_cvt_pk_bf16_f32 v188, v168, v169
	v_cvt_pk_bf16_f32 v189, v170, v171
	v_mov_b32_e32 v2, 0
	s_cmp_eq_u32 s89, 1
	s_cbranch_scc1 .Latt_w14_20
	s_waitcnt vmcnt(12)
	s_branch .Latt_wj_21
.Latt_w14_20:
	s_waitcnt vmcnt(10)

.Latt_half_22:
	s_add_i32 s7, s5, 128
	s_and_b32 s7, s7, 511
	s_lshl_b32 s7, s7, 7
	s_add_i32 m0, s7, s49
	s_add_i32 s7, s6, 128
	v_add_u32_e32 v0, s7, v14
	v_lshlrev_b32_e32 v0, s28, v0
	v_add_u32_e32 v0, s29, v0
	v_max_i32_e32 v0, 0, v0
	v_lshl_or_b32 v2, v0, 7, v15
	v_lshl_add_u64 v[42:43], s[50:51], 0, v[2:3]
	global_load_lds_dwordx4 v[42:43], off nt
	s_add_i32 s7, s5, 192
	s_and_b32 s7, s7, 511
	s_lshl_b32 s7, s7, 7
	s_add_i32 m0, s7, s49
	s_add_i32 s7, s6, 192
	v_add_u32_e32 v0, s7, v14
	v_lshlrev_b32_e32 v0, s28, v0
	v_add_u32_e32 v0, s29, v0
	v_max_i32_e32 v0, 0, v0
	v_lshl_or_b32 v2, v0, 7, v15
	v_lshl_add_u64 v[44:45], s[50:51], 0, v[2:3]
	global_load_lds_dwordx4 v[44:45], off nt
	s_add_i32 s4, s53, 2
	s_min_u32 s4, s4, 47
	s_lshr_b32 s11, s4, 4
	s_and_b32 s12, s4, 15
	s_lshl_b32 s8, s11, 1
	s_lshl_b32 s13, s64, 4
	s_add_i32 s13, s13, s12
	s_lshr_b32 s14, s12, 2
	s_and_b32 s15, s12, 3
	s_lshl_b32 s16, s64, 2
	s_add_i32 s15, s16, s15
	s_cmp_eq_u32 s11, 1
	s_cselect_b32 s17, s14, 0
	s_cselect_b32 s10, s15, s13
	s_cmp_eq_u32 s11, 2
	s_cselect_b32 s17, s12, s17
	s_cselect_b32 s10, s64, s10
	s_lshl_b32 s5, s10, 7
	v_add_u32_e32 v82, s5, v17
	v_lshlrev_b32_e32 v82, s8, v82
	v_add_u32_e32 v82, s17, v82
	v_lshl_add_u32 v1, v82, 11, v18
	global_load_dwordx4 v[48:51], v1, s[40:41]
	global_load_dwordx4 v[52:55], v1, s[40:41] offset:64
	s_add_i32 s5, s91, 0
	s_and_b32 s5, s5, 31
	s_lshl_b32 s5, s5, 11
	v_add_u32_e32 v37, s5, v6
	v_add_u32_e32 v38, s5, v7
	v_add_u32_e32 v39, s5, v8
	v_add_u32_e32 v40, s5, v9
	ds_read_b64_tr_b16 v[84:85], v37
	ds_read_b64_tr_b16 v[88:89], v38
	ds_read_b64_tr_b16 v[92:93], v39
	ds_read_b64_tr_b16 v[96:97], v40
	s_add_i32 s5, s91, 1
	s_and_b32 s5, s5, 31
	s_lshl_b32 s5, s5, 11
	v_add_u32_e32 v37, s5, v6
	v_add_u32_e32 v38, s5, v7
	v_add_u32_e32 v39, s5, v8
	v_add_u32_e32 v40, s5, v9
	ds_read_b64_tr_b16 v[86:87], v37
	ds_read_b64_tr_b16 v[90:91], v38
	ds_read_b64_tr_b16 v[94:95], v39
	ds_read_b64_tr_b16 v[98:99], v40
	s_add_i32 s5, s91, 2
	s_and_b32 s5, s5, 31
	s_lshl_b32 s5, s5, 11
	v_add_u32_e32 v37, s5, v6
	v_add_u32_e32 v38, s5, v7
	v_add_u32_e32 v39, s5, v8
	v_add_u32_e32 v40, s5, v9
	ds_read_b64_tr_b16 v[100:101], v37
	ds_read_b64_tr_b16 v[104:105], v38
	ds_read_b64_tr_b16 v[108:109], v39
	ds_read_b64_tr_b16 v[112:113], v40
	s_add_i32 s5, s91, 3
	s_and_b32 s5, s5, 31
	s_lshl_b32 s5, s5, 11
	v_add_u32_e32 v37, s5, v6
	v_add_u32_e32 v38, s5, v7
	v_add_u32_e32 v39, s5, v8
	v_add_u32_e32 v40, s5, v9
	ds_read_b64_tr_b16 v[102:103], v37
	ds_read_b64_tr_b16 v[106:107], v38
	ds_read_b64_tr_b16 v[110:111], v39
	ds_read_b64_tr_b16 v[114:115], v40
	s_waitcnt lgkmcnt(8)
	v_mfma_f32_16x16x32_bf16 v[228:231], v[84:87], v[172:175], 0
	v_mfma_f32_16x16x32_bf16 v[232:235], v[88:91], v[172:175], 0
	v_mfma_f32_16x16x32_bf16 v[236:239], v[92:95], v[172:175], 0
	v_mfma_f32_16x16x32_bf16 v[240:243], v[96:99], v[172:175], 0
	s_add_i32 s5, s91, 4
	s_and_b32 s5, s5, 31
	s_lshl_b32 s5, s5, 11
	v_add_u32_e32 v37, s5, v6
	v_add_u32_e32 v38, s5, v7
	v_add_u32_e32 v39, s5, v8
	v_add_u32_e32 v40, s5, v9
	ds_read_b64_tr_b16 v[84:85], v37
	ds_read_b64_tr_b16 v[88:89], v38
	ds_read_b64_tr_b16 v[92:93], v39
	ds_read_b64_tr_b16 v[96:97], v40
	s_add_i32 s5, s91, 5
	s_and_b32 s5, s5, 31
	s_lshl_b32 s5, s5, 11
	v_add_u32_e32 v37, s5, v6
	v_add_u32_e32 v38, s5, v7
	v_add_u32_e32 v39, s5, v8
	v_add_u32_e32 v40, s5, v9
	ds_read_b64_tr_b16 v[86:87], v37
	ds_read_b64_tr_b16 v[90:91], v38
	ds_read_b64_tr_b16 v[94:95], v39
	ds_read_b64_tr_b16 v[98:99], v40
	s_waitcnt lgkmcnt(8)
	v_mfma_f32_16x16x32_bf16 v[228:231], v[100:103], v[176:179], v[228:231]
	v_mfma_f32_16x16x32_bf16 v[232:235], v[104:107], v[176:179], v[232:235]
	v_mfma_f32_16x16x32_bf16 v[236:239], v[108:111], v[176:179], v[236:239]
	v_mfma_f32_16x16x32_bf16 v[240:243], v[112:115], v[176:179], v[240:243]
	s_add_i32 s5, s91, 6
	s_and_b32 s5, s5, 31
	s_lshl_b32 s5, s5, 11
	v_add_u32_e32 v37, s5, v6
	v_add_u32_e32 v38, s5, v7
	v_add_u32_e32 v39, s5, v8
	v_add_u32_e32 v40, s5, v9
	ds_read_b64_tr_b16 v[100:101], v37
	ds_read_b64_tr_b16 v[104:105], v38
	ds_read_b64_tr_b16 v[108:109], v39
	ds_read_b64_tr_b16 v[112:113], v40
	s_add_i32 s5, s91, 7
	s_and_b32 s5, s5, 31
	s_lshl_b32 s5, s5, 11
	v_add_u32_e32 v37, s5, v6
	v_add_u32_e32 v38, s5, v7
	v_add_u32_e32 v39, s5, v8
	v_add_u32_e32 v40, s5, v9
	ds_read_b64_tr_b16 v[102:103], v37
	ds_read_b64_tr_b16 v[106:107], v38
	ds_read_b64_tr_b16 v[110:111], v39
	ds_read_b64_tr_b16 v[114:115], v40
	s_waitcnt lgkmcnt(8)
	v_mfma_f32_16x16x32_bf16 v[228:231], v[84:87], v[180:183], v[228:231]
	v_mfma_f32_16x16x32_bf16 v[232:235], v[88:91], v[180:183], v[232:235]
	v_mfma_f32_16x16x32_bf16 v[236:239], v[92:95], v[180:183], v[236:239]
	v_mfma_f32_16x16x32_bf16 v[240:243], v[96:99], v[180:183], v[240:243]
	s_add_i32 s5, s91, 8
	s_and_b32 s5, s5, 31
	s_lshl_b32 s5, s5, 11
	v_add_u32_e32 v37, s5, v6
	v_add_u32_e32 v38, s5, v7
	v_add_u32_e32 v39, s5, v8
	v_add_u32_e32 v40, s5, v9
	ds_read_b64_tr_b16 v[84:85], v37
	ds_read_b64_tr_b16 v[88:89], v38
	ds_read_b64_tr_b16 v[92:93], v39
	ds_read_b64_tr_b16 v[96:97], v40
	s_add_i32 s5, s67, 9
	s_min_u32 s5, s5, 15
	s_lshl_b32 s6, s90, 3
	s_add_i32 s5, s5, s6
	s_and_b32 s5, s5, 31
	s_lshl_b32 s5, s5, 11
	v_add_u32_e32 v37, s5, v6
	v_add_u32_e32 v38, s5, v7
	v_add_u32_e32 v39, s5, v8
	v_add_u32_e32 v40, s5, v9
	ds_read_b64_tr_b16 v[86:87], v37
	ds_read_b64_tr_b16 v[90:91], v38
	ds_read_b64_tr_b16 v[94:95], v39
	ds_read_b64_tr_b16 v[98:99], v40
	s_waitcnt lgkmcnt(8)
	v_mfma_f32_16x16x32_bf16 v[228:231], v[100:103], v[184:187], v[228:231]
	v_mfma_f32_16x16x32_bf16 v[232:235], v[104:107], v[184:187], v[232:235]
	v_mfma_f32_16x16x32_bf16 v[236:239], v[108:111], v[184:187], v[236:239]
	v_mfma_f32_16x16x32_bf16 v[240:243], v[112:115], v[184:187], v[240:243]
	s_waitcnt lgkmcnt(0)
	v_mfma_f32_16x16x32_bf16 v[228:231], v[84:87], v[188:191], v[228:231]
	v_mfma_f32_16x16x32_bf16 v[232:235], v[88:91], v[188:191], v[232:235]
	v_mfma_f32_16x16x32_bf16 v[236:239], v[92:95], v[188:191], v[236:239]
	v_mfma_f32_16x16x32_bf16 v[240:243], v[96:99], v[188:191], v[240:243]
	v_mov_b32_e32 v0, v36
	v_mov_b32_e32 v1, v36
	s_nop 1
	v_permlane16_swap_b32_e32 v0, v1
	s_nop 1
	v_add_f32_e32 v36, v0, v1
	v_mov_b32_e32 v0, v36
	v_mov_b32_e32 v1, v36
	s_nop 1
	v_permlane32_swap_b32_e32 v0, v1
	s_nop 1
	v_add_f32_e32 v36, v0, v1
	s_cmp_lt_u32 s53, 16
	s_cbranch_scc0 .Latt_hasprev_23
	v_mov_b32_e32 v80, v223
	v_mov_b32_e32 v64, 0
	v_mov_b32_e32 v65, 0
	v_mov_b32_e32 v66, 0
	v_mov_b32_e32 v67, 0
	v_mov_b32_e32 v68, 0
	v_mov_b32_e32 v69, 0
	v_mov_b32_e32 v70, 0
	v_mov_b32_e32 v71, 0
	s_branch .Latt_noprev_24
.Latt_hasprev_23:
	v_permlane16_swap_b32_e32 v64, v66
	v_permlane16_swap_b32_e32 v65, v67
	v_permlane16_swap_b32_e32 v68, v70
	v_permlane16_swap_b32_e32 v69, v71
.Latt_noprev_24:
	v_max_f32_e32 v116, v80, v35
	v_sub_f32_e32 v117, v80, v116
	v_sub_f32_e32 v118, v35, v116
	v_exp_f32_e32 v117, v117
	v_exp_f32_e32 v118, v118
	s_lshl_b32 s5, s24, 7
	v_add_u32_e32 v83, s5, v17
	v_lshlrev_b32_e32 v83, s20, v83
	v_add_u32_e32 v83, s21, v83
	v_fma_f32 v119, v36, v118, v117
	v_rcp_f32_e32 v122, v119
	v_lshl_add_u32 v123, v83, 11, v19
	s_nop 0
	v_mul_f32_e32 v120, v117, v122
	v_mul_f32_e32 v121, v118, v122
	v_lshlrev_b32_e32 v124, 16, v64
	v_and_b32_e32 v125, 0xffff0000, v64
	v_lshlrev_b32_e32 v126, 16, v65
	v_and_b32_e32 v127, 0xffff0000, v65
	v_mul_f32_e32 v124, v120, v124
	v_mul_f32_e32 v125, v120, v125
	v_mul_f32_e32 v126, v120, v126
	v_mul_f32_e32 v127, v120, v127
	v_fma_f32 v124, v228, v121, v124
	v_fma_f32 v125, v229, v121, v125
	v_fma_f32 v126, v230, v121, v126
	v_fma_f32 v127, v231, v121, v127
	v_cvt_pk_bf16_f32 v84, v124, v125
	v_cvt_pk_bf16_f32 v85, v126, v127
	v_lshlrev_b32_e32 v124, 16, v66
	v_and_b32_e32 v125, 0xffff0000, v66
	v_lshlrev_b32_e32 v126, 16, v67
	v_and_b32_e32 v127, 0xffff0000, v67
	v_mul_f32_e32 v124, v120, v124
	v_mul_f32_e32 v125, v120, v125
	v_mul_f32_e32 v126, v120, v126
	v_mul_f32_e32 v127, v120, v127
	v_fma_f32 v124, v232, v121, v124
	v_fma_f32 v125, v233, v121, v125
	v_fma_f32 v126, v234, v121, v126
	v_fma_f32 v127, v235, v121, v127
	v_cvt_pk_bf16_f32 v86, v124, v125
	v_cvt_pk_bf16_f32 v87, v126, v127
	v_lshlrev_b32_e32 v124, 16, v68
	v_and_b32_e32 v125, 0xffff0000, v68
	v_lshlrev_b32_e32 v126, 16, v69
	v_and_b32_e32 v127, 0xffff0000, v69
	v_mul_f32_e32 v124, v120, v124
	v_mul_f32_e32 v125, v120, v125
	v_mul_f32_e32 v126, v120, v126
	v_mul_f32_e32 v127, v120, v127
	v_fma_f32 v124, v236, v121, v124
	v_fma_f32 v125, v237, v121, v125
	v_fma_f32 v126, v238, v121, v126
	v_fma_f32 v127, v239, v121, v127
	v_cvt_pk_bf16_f32 v88, v124, v125
	v_cvt_pk_bf16_f32 v89, v126, v127
	v_lshlrev_b32_e32 v124, 16, v70
	v_and_b32_e32 v125, 0xffff0000, v70
	v_lshlrev_b32_e32 v126, 16, v71
	v_and_b32_e32 v127, 0xffff0000, v71
	v_mul_f32_e32 v124, v120, v124
	v_mul_f32_e32 v125, v120, v125
	v_mul_f32_e32 v126, v120, v126
	v_mul_f32_e32 v127, v120, v127
	v_fma_f32 v124, v240, v121, v124
	v_fma_f32 v125, v241, v121, v125
	v_fma_f32 v126, v242, v121, v126
	v_fma_f32 v127, v243, v121, v127
	v_cvt_pk_bf16_f32 v90, v124, v125
	v_cvt_pk_bf16_f32 v91, v126, v127
	s_nop 1
	v_permlane16_swap_b32_e32 v84, v86
	v_permlane16_swap_b32_e32 v85, v87
	v_permlane16_swap_b32_e32 v88, v90
	v_permlane16_swap_b32_e32 v89, v91
	global_store_dwordx4 v123, v[84:87], s[42:43] offset:0
	global_store_dwordx4 v123, v[88:91], s[42:43] offset:64
	v_log_f32_e32 v130, v119
	v_lshlrev_b32_e32 v131, 2, v83
	s_nop 0
	v_add_f32_e32 v130, v116, v130
	s_mov_b64 exec, 0xffff
	global_store_dword v131, v130, s[44:45]
	s_mov_b64 exec, -1
	s_cmp_lt_u32 s4, 16
	s_cbranch_scc1 .Latt_odummy_25
	v_lshl_add_u32 v1, v82, 11, v19
	global_load_dwordx4 v[64:67], v1, s[42:43] offset:0
	global_load_dwordx4 v[68:71], v1, s[42:43] offset:64
	v_lshlrev_b32_e32 v0, 2, v82
	global_load_dword v80, v0, s[44:45]
	s_branch .Latt_odone_26

.Latt_odone_26:
	s_cmp_eq_u32 s89, 1
	s_cbranch_scc1 .Latt_w14_27
	s_waitcnt vmcnt(12)
	s_branch .Latt_wj_28

.Latt_n0t_38:
.Latt_n0skip_30:
	s_waitcnt lgkmcnt(10)
	v_mfma_f32_16x16x32_bf16 v[132:135], v[84:87], v[56:59], v[22:25]
	v_mfma_f32_16x16x32_bf16 v[132:135], v[88:91], v[60:63], v[132:135]
	s_waitcnt lgkmcnt(8)
	v_mfma_f32_16x16x32_bf16 v[136:139], v[92:95], v[56:59], v[22:25]
	v_mfma_f32_16x16x32_bf16 v[136:139], v[96:99], v[60:63], v[136:139]
	s_waitcnt lgkmcnt(6)
	v_mfma_f32_16x16x32_bf16 v[140:143], v[100:103], v[56:59], v[22:25]
	v_mfma_f32_16x16x32_bf16 v[140:143], v[104:107], v[60:63], v[140:143]
	s_add_i32 s5, s91, 6
	s_and_b32 s5, s5, 31
	s_lshl_b32 s5, s5, 11
	v_add_u32_e32 v0, s5, v4
	v_add_u32_e32 v1, s5, v5
	ds_read_b128 v[84:87], v0
	ds_read_b128 v[88:91], v1
	s_add_i32 s5, s91, 7
	s_and_b32 s5, s5, 31
	s_lshl_b32 s5, s5, 11
	v_add_u32_e32 v0, s5, v4
	v_add_u32_e32 v1, s5, v5
	ds_read_b128 v[92:95], v0
	ds_read_b128 v[96:99], v1
	s_add_i32 s5, s91, 8
	s_and_b32 s5, s5, 31
	s_lshl_b32 s5, s5, 11
	v_add_u32_e32 v0, s5, v4
	v_add_u32_e32 v1, s5, v5
	ds_read_b128 v[100:103], v0
	ds_read_b128 v[104:107], v1
	s_waitcnt lgkmcnt(10)
	v_mfma_f32_16x16x32_bf16 v[144:147], v[108:111], v[56:59], v[22:25]
	v_mfma_f32_16x16x32_bf16 v[144:147], v[112:115], v[60:63], v[144:147]
	s_waitcnt lgkmcnt(8)
	v_mfma_f32_16x16x32_bf16 v[148:151], v[116:119], v[56:59], v[22:25]
	v_mfma_f32_16x16x32_bf16 v[148:151], v[120:123], v[60:63], v[148:151]
	s_waitcnt lgkmcnt(6)
	v_mfma_f32_16x16x32_bf16 v[152:155], v[124:127], v[56:59], v[22:25]
	v_mfma_f32_16x16x32_bf16 v[152:155], v[128:131], v[60:63], v[152:155]
	s_waitcnt lgkmcnt(4)
	v_mfma_f32_16x16x32_bf16 v[160:163], v[84:87], v[56:59], v[22:25]
	v_mfma_f32_16x16x32_bf16 v[160:163], v[88:91], v[60:63], v[160:163]
	s_waitcnt lgkmcnt(2)
	v_mfma_f32_16x16x32_bf16 v[164:167], v[92:95], v[56:59], v[22:25]
	v_mfma_f32_16x16x32_bf16 v[164:167], v[96:99], v[60:63], v[164:167]
	s_waitcnt lgkmcnt(0)
	v_mfma_f32_16x16x32_bf16 v[168:171], v[100:103], v[56:59], v[22:25]
	v_mfma_f32_16x16x32_bf16 v[168:171], v[104:107], v[60:63], v[168:171]
	s_nop 7
	s_nop 3
	v_cndmask_b32_e64 v132, v132, v223, s[54:55]
	v_cndmask_b32_e64 v133, v133, v223, s[56:57]
	v_cndmask_b32_e64 v134, v134, v223, s[58:59]
	v_cndmask_b32_e64 v135, v135, v223, s[60:61]
	v_cndmask_b32_e64 v168, v168, v223, s[70:71]
	v_cndmask_b32_e64 v169, v169, v223, s[72:73]
	v_cndmask_b32_e64 v170, v170, v223, s[74:75]
	v_cndmask_b32_e64 v171, v171, v223, s[76:77]
	v_max3_f32 v0, v132, v133, v134
	v_max_f32_e32 v0, v0, v135
	v_add_f32_e32 v35, v0, v26
	v_max3_f32 v0, v136, v137, v138
	v_max_f32_e32 v0, v0, v139
	v_add_f32_e32 v0, v0, v27
	v_max_f32_e32 v35, v35, v0
	v_max3_f32 v0, v140, v141, v142
	v_max_f32_e32 v0, v0, v143
	v_add_f32_e32 v0, v0, v28
	v_max_f32_e32 v35, v35, v0
	v_max3_f32 v0, v144, v145, v146
	v_max_f32_e32 v0, v0, v147
	v_add_f32_e32 v0, v0, v29
	v_max_f32_e32 v35, v35, v0
	v_max3_f32 v0, v148, v149, v150
	v_max_f32_e32 v0, v0, v151
	v_add_f32_e32 v0, v0, v30
	v_max_f32_e32 v35, v35, v0
	v_max3_f32 v0, v152, v153, v154
	v_max_f32_e32 v0, v0, v155
	v_add_f32_e32 v0, v0, v31
	v_max_f32_e32 v35, v35, v0
	v_max3_f32 v0, v160, v161, v162
	v_max_f32_e32 v0, v0, v163
	v_add_f32_e32 v0, v0, v32
	v_max_f32_e32 v35, v35, v0
	v_max3_f32 v0, v164, v165, v166
	v_max_f32_e32 v0, v0, v167
	v_add_f32_e32 v0, v0, v33
	v_max_f32_e32 v35, v35, v0
	v_max3_f32 v0, v168, v169, v170
	v_max_f32_e32 v0, v0, v171
	v_add_f32_e32 v0, v0, v34
	v_max_f32_e32 v35, v35, v0
	v_mov_b32_e32 v0, v35
	v_mov_b32_e32 v1, v35
	s_nop 1
	v_permlane16_swap_b32_e32 v0, v1
	s_nop 1
	v_max_f32_e32 v35, v0, v1
	v_mov_b32_e32 v0, v35
	v_mov_b32_e32 v1, v35
	s_nop 1
	v_permlane32_swap_b32_e32 v0, v1
	s_nop 1
	v_max_f32_e32 v35, v0, v1
	v_sub_f32_e32 v2, v26, v35
	v_add_f32_e32 v132, v132, v2
	v_add_f32_e32 v133, v133, v2
	v_add_f32_e32 v134, v134, v2
	v_add_f32_e32 v135, v135, v2
	v_exp_f32_e32 v132, v132
	v_exp_f32_e32 v133, v133
	v_exp_f32_e32 v134, v134
	v_exp_f32_e32 v135, v135
	v_add_f32_e32 v36, 0, v132
	v_add_f32_e32 v36, v133, v36
	v_add_f32_e32 v36, v134, v36
	v_add_f32_e32 v36, v135, v36
	v_cvt_pk_bf16_f32 v172, v132, v133
	v_cvt_pk_bf16_f32 v173, v134, v135
	v_sub_f32_e32 v2, v27, v35
	v_add_f32_e32 v136, v136, v2
	v_add_f32_e32 v137, v137, v2
	v_add_f32_e32 v138, v138, v2
	v_add_f32_e32 v139, v139, v2
	v_exp_f32_e32 v136, v136
	v_exp_f32_e32 v137, v137
	v_exp_f32_e32 v138, v138
	v_exp_f32_e32 v139, v139
	v_add_f32_e32 v36, v136, v36
	v_add_f32_e32 v36, v137, v36
	v_add_f32_e32 v36, v138, v36
	v_add_f32_e32 v36, v139, v36
	v_cvt_pk_bf16_f32 v174, v136, v137
	v_cvt_pk_bf16_f32 v175, v138, v139
	v_sub_f32_e32 v2, v28, v35
	v_add_f32_e32 v140, v140, v2
	v_add_f32_e32 v141, v141, v2
	v_add_f32_e32 v142, v142, v2
	v_add_f32_e32 v143, v143, v2
	v_exp_f32_e32 v140, v140
	v_exp_f32_e32 v141, v141
	v_exp_f32_e32 v142, v142
	v_exp_f32_e32 v143, v143
	v_add_f32_e32 v36, v140, v36
	v_add_f32_e32 v36, v141, v36
	v_add_f32_e32 v36, v142, v36
	v_add_f32_e32 v36, v143, v36
	v_cvt_pk_bf16_f32 v176, v140, v141
	v_cvt_pk_bf16_f32 v177, v142, v143
	v_sub_f32_e32 v2, v29, v35
	v_add_f32_e32 v144, v144, v2
	v_add_f32_e32 v145, v145, v2
	v_add_f32_e32 v146, v146, v2
	v_add_f32_e32 v147, v147, v2
	v_exp_f32_e32 v144, v144
	v_exp_f32_e32 v145, v145
	v_exp_f32_e32 v146, v146
	v_exp_f32_e32 v147, v147
	v_add_f32_e32 v36, v144, v36
	v_add_f32_e32 v36, v145, v36
	v_add_f32_e32 v36, v146, v36
	v_add_f32_e32 v36, v147, v36
	v_cvt_pk_bf16_f32 v178, v144, v145
	v_cvt_pk_bf16_f32 v179, v146, v147
	v_sub_f32_e32 v2, v30, v35
	v_add_f32_e32 v148, v148, v2
	v_add_f32_e32 v149, v149, v2
	v_add_f32_e32 v150, v150, v2
	v_add_f32_e32 v151, v151, v2
	v_exp_f32_e32 v148, v148
	v_exp_f32_e32 v149, v149
	v_exp_f32_e32 v150, v150
	v_exp_f32_e32 v151, v151
	v_add_f32_e32 v36, v148, v36
	v_add_f32_e32 v36, v149, v36
	v_add_f32_e32 v36, v150, v36
	v_add_f32_e32 v36, v151, v36
	v_cvt_pk_bf16_f32 v180, v148, v149
	v_cvt_pk_bf16_f32 v181, v150, v151
	v_sub_f32_e32 v2, v31, v35
	v_add_f32_e32 v152, v152, v2
	v_add_f32_e32 v153, v153, v2
	v_add_f32_e32 v154, v154, v2
	v_add_f32_e32 v155, v155, v2
	v_exp_f32_e32 v152, v152
	v_exp_f32_e32 v153, v153
	v_exp_f32_e32 v154, v154
	v_exp_f32_e32 v155, v155
	v_add_f32_e32 v36, v152, v36
	v_add_f32_e32 v36, v153, v36
	v_add_f32_e32 v36, v154, v36
	v_add_f32_e32 v36, v155, v36
	v_cvt_pk_bf16_f32 v182, v152, v153
	v_cvt_pk_bf16_f32 v183, v154, v155
	v_sub_f32_e32 v2, v32, v35
	v_add_f32_e32 v160, v160, v2
	v_add_f32_e32 v161, v161, v2
	v_add_f32_e32 v162, v162, v2
	v_add_f32_e32 v163, v163, v2
	v_exp_f32_e32 v160, v160
	v_exp_f32_e32 v161, v161
	v_exp_f32_e32 v162, v162
	v_exp_f32_e32 v163, v163
	v_add_f32_e32 v36, v160, v36
	v_add_f32_e32 v36, v161, v36
	v_add_f32_e32 v36, v162, v36
	v_add_f32_e32 v36, v163, v36
	v_cvt_pk_bf16_f32 v184, v160, v161
	v_cvt_pk_bf16_f32 v185, v162, v163
	v_sub_f32_e32 v2, v33, v35
	v_add_f32_e32 v164, v164, v2
	v_add_f32_e32 v165, v165, v2
	v_add_f32_e32 v166, v166, v2
	v_add_f32_e32 v167, v167, v2
	v_exp_f32_e32 v164, v164
	v_exp_f32_e32 v165, v165
	v_exp_f32_e32 v166, v166
	v_exp_f32_e32 v167, v167
	v_add_f32_e32 v36, v164, v36
	v_add_f32_e32 v36, v165, v36
	v_add_f32_e32 v36, v166, v36
	v_add_f32_e32 v36, v167, v36
	v_cvt_pk_bf16_f32 v186, v164, v165
	v_cvt_pk_bf16_f32 v187, v166, v167
	v_sub_f32_e32 v2, v34, v35
	v_add_f32_e32 v168, v168, v2
	v_add_f32_e32 v169, v169, v2
	v_add_f32_e32 v170, v170, v2
	v_add_f32_e32 v171, v171, v2
	v_exp_f32_e32 v168, v168
	v_exp_f32_e32 v169, v169
	v_exp_f32_e32 v170, v170
	v_exp_f32_e32 v171, v171
	v_add_f32_e32 v36, v168, v36
	v_add_f32_e32 v36, v169, v36
	v_add_f32_e32 v36, v170, v36
	v_add_f32_e32 v36, v171, v36
	v_cvt_pk_bf16_f32 v188, v168, v169
	v_cvt_pk_bf16_f32 v189, v170, v171
	v_mov_b32_e32 v2, 0
	s_cmp_eq_u32 s89, 1
	s_cbranch_scc1 .Latt_w14_39
	s_waitcnt vmcnt(12)
	s_branch .Latt_wj_40

.Latt_half_41:
	s_add_i32 s7, s5, 128
	s_and_b32 s7, s7, 511
	s_lshl_b32 s7, s7, 7
	s_add_i32 m0, s7, s49
	s_add_i32 s7, s6, 128
	v_add_u32_e32 v0, s7, v14
	v_lshlrev_b32_e32 v0, s28, v0
	v_add_u32_e32 v0, s29, v0
	v_max_i32_e32 v0, 0, v0
	v_lshl_or_b32 v2, v0, 7, v15
	v_lshl_add_u64 v[42:43], s[50:51], 0, v[2:3]
	global_load_lds_dwordx4 v[42:43], off nt
	s_add_i32 s7, s5, 192
	s_and_b32 s7, s7, 511
	s_lshl_b32 s7, s7, 7
	s_add_i32 m0, s7, s49
	s_add_i32 s7, s6, 192
	v_add_u32_e32 v0, s7, v14
	v_lshlrev_b32_e32 v0, s28, v0
	v_add_u32_e32 v0, s29, v0
	v_max_i32_e32 v0, 0, v0
	v_lshl_or_b32 v2, v0, 7, v15
	v_lshl_add_u64 v[44:45], s[50:51], 0, v[2:3]
	global_load_lds_dwordx4 v[44:45], off nt
	s_add_i32 s4, s9, 2
	s_min_u32 s4, s4, 47
	s_lshr_b32 s11, s4, 4
	s_and_b32 s12, s4, 15
	s_lshl_b32 s8, s11, 1
	s_lshl_b32 s13, s64, 4
	s_add_i32 s13, s13, s12
	s_lshr_b32 s14, s12, 2
	s_and_b32 s15, s12, 3
	s_lshl_b32 s16, s64, 2
	s_add_i32 s15, s16, s15
	s_cmp_eq_u32 s11, 1
	s_cselect_b32 s17, s14, 0
	s_cselect_b32 s10, s15, s13
	s_cmp_eq_u32 s11, 2
	s_cselect_b32 s17, s12, s17
	s_cselect_b32 s10, s64, s10
	s_lshl_b32 s5, s10, 7
	v_add_u32_e32 v82, s5, v17
	v_lshlrev_b32_e32 v82, s8, v82
	v_add_u32_e32 v82, s17, v82
	v_lshl_add_u32 v1, v82, 11, v18
	global_load_dwordx4 v[56:59], v1, s[40:41]
	global_load_dwordx4 v[60:63], v1, s[40:41] offset:64
	s_add_i32 s5, s91, 0
	s_and_b32 s5, s5, 31
	s_lshl_b32 s5, s5, 11
	v_add_u32_e32 v37, s5, v6
	v_add_u32_e32 v38, s5, v7
	v_add_u32_e32 v39, s5, v8
	v_add_u32_e32 v40, s5, v9
	ds_read_b64_tr_b16 v[84:85], v37
	ds_read_b64_tr_b16 v[88:89], v38
	ds_read_b64_tr_b16 v[92:93], v39
	ds_read_b64_tr_b16 v[96:97], v40
	s_add_i32 s5, s91, 1
	s_and_b32 s5, s5, 31
	s_lshl_b32 s5, s5, 11
	v_add_u32_e32 v37, s5, v6
	v_add_u32_e32 v38, s5, v7
	v_add_u32_e32 v39, s5, v8
	v_add_u32_e32 v40, s5, v9
	ds_read_b64_tr_b16 v[86:87], v37
	ds_read_b64_tr_b16 v[90:91], v38
	ds_read_b64_tr_b16 v[94:95], v39
	ds_read_b64_tr_b16 v[98:99], v40
	s_add_i32 s5, s91, 2
	s_and_b32 s5, s5, 31
	s_lshl_b32 s5, s5, 11
	v_add_u32_e32 v37, s5, v6
	v_add_u32_e32 v38, s5, v7
	v_add_u32_e32 v39, s5, v8
	v_add_u32_e32 v40, s5, v9
	ds_read_b64_tr_b16 v[100:101], v37
	ds_read_b64_tr_b16 v[104:105], v38
	ds_read_b64_tr_b16 v[108:109], v39
	ds_read_b64_tr_b16 v[112:113], v40
	s_add_i32 s5, s91, 3
	s_and_b32 s5, s5, 31
	s_lshl_b32 s5, s5, 11
	v_add_u32_e32 v37, s5, v6
	v_add_u32_e32 v38, s5, v7
	v_add_u32_e32 v39, s5, v8
	v_add_u32_e32 v40, s5, v9
	ds_read_b64_tr_b16 v[102:103], v37
	ds_read_b64_tr_b16 v[106:107], v38
	ds_read_b64_tr_b16 v[110:111], v39
	ds_read_b64_tr_b16 v[114:115], v40
	s_waitcnt lgkmcnt(8)
	v_mfma_f32_16x16x32_bf16 v[228:231], v[84:87], v[172:175], 0
	v_mfma_f32_16x16x32_bf16 v[232:235], v[88:91], v[172:175], 0
	v_mfma_f32_16x16x32_bf16 v[236:239], v[92:95], v[172:175], 0
	v_mfma_f32_16x16x32_bf16 v[240:243], v[96:99], v[172:175], 0
	s_add_i32 s5, s91, 4
	s_and_b32 s5, s5, 31
	s_lshl_b32 s5, s5, 11
	v_add_u32_e32 v37, s5, v6
	v_add_u32_e32 v38, s5, v7
	v_add_u32_e32 v39, s5, v8
	v_add_u32_e32 v40, s5, v9
	ds_read_b64_tr_b16 v[84:85], v37
	ds_read_b64_tr_b16 v[88:89], v38
	ds_read_b64_tr_b16 v[92:93], v39
	ds_read_b64_tr_b16 v[96:97], v40
	s_add_i32 s5, s91, 5
	s_and_b32 s5, s5, 31
	s_lshl_b32 s5, s5, 11
	v_add_u32_e32 v37, s5, v6
	v_add_u32_e32 v38, s5, v7
	v_add_u32_e32 v39, s5, v8
	v_add_u32_e32 v40, s5, v9
	ds_read_b64_tr_b16 v[86:87], v37
	ds_read_b64_tr_b16 v[90:91], v38
	ds_read_b64_tr_b16 v[94:95], v39
	ds_read_b64_tr_b16 v[98:99], v40
	s_waitcnt lgkmcnt(8)
	v_mfma_f32_16x16x32_bf16 v[228:231], v[100:103], v[176:179], v[228:231]
	v_mfma_f32_16x16x32_bf16 v[232:235], v[104:107], v[176:179], v[232:235]
	v_mfma_f32_16x16x32_bf16 v[236:239], v[108:111], v[176:179], v[236:239]
	v_mfma_f32_16x16x32_bf16 v[240:243], v[112:115], v[176:179], v[240:243]
	s_add_i32 s5, s91, 6
	s_and_b32 s5, s5, 31
	s_lshl_b32 s5, s5, 11
	v_add_u32_e32 v37, s5, v6
	v_add_u32_e32 v38, s5, v7
	v_add_u32_e32 v39, s5, v8
	v_add_u32_e32 v40, s5, v9
	ds_read_b64_tr_b16 v[100:101], v37
	ds_read_b64_tr_b16 v[104:105], v38
	ds_read_b64_tr_b16 v[108:109], v39
	ds_read_b64_tr_b16 v[112:113], v40
	s_add_i32 s5, s91, 7
	s_and_b32 s5, s5, 31
	s_lshl_b32 s5, s5, 11
	v_add_u32_e32 v37, s5, v6
	v_add_u32_e32 v38, s5, v7
	v_add_u32_e32 v39, s5, v8
	v_add_u32_e32 v40, s5, v9
	ds_read_b64_tr_b16 v[102:103], v37
	ds_read_b64_tr_b16 v[106:107], v38
	ds_read_b64_tr_b16 v[110:111], v39
	ds_read_b64_tr_b16 v[114:115], v40
	s_waitcnt lgkmcnt(8)
	v_mfma_f32_16x16x32_bf16 v[228:231], v[84:87], v[180:183], v[228:231]
	v_mfma_f32_16x16x32_bf16 v[232:235], v[88:91], v[180:183], v[232:235]
	v_mfma_f32_16x16x32_bf16 v[236:239], v[92:95], v[180:183], v[236:239]
	v_mfma_f32_16x16x32_bf16 v[240:243], v[96:99], v[180:183], v[240:243]
	s_add_i32 s5, s91, 8
	s_and_b32 s5, s5, 31
	s_lshl_b32 s5, s5, 11
	v_add_u32_e32 v37, s5, v6
	v_add_u32_e32 v38, s5, v7
	v_add_u32_e32 v39, s5, v8
	v_add_u32_e32 v40, s5, v9
	ds_read_b64_tr_b16 v[84:85], v37
	ds_read_b64_tr_b16 v[88:89], v38
	ds_read_b64_tr_b16 v[92:93], v39
	ds_read_b64_tr_b16 v[96:97], v40
	s_add_i32 s5, s67, 9
	s_min_u32 s5, s5, 15
	s_lshl_b32 s6, s90, 3
	s_add_i32 s5, s5, s6
	s_and_b32 s5, s5, 31
	s_lshl_b32 s5, s5, 11
	v_add_u32_e32 v37, s5, v6
	v_add_u32_e32 v38, s5, v7
	v_add_u32_e32 v39, s5, v8
	v_add_u32_e32 v40, s5, v9
	ds_read_b64_tr_b16 v[86:87], v37
	ds_read_b64_tr_b16 v[90:91], v38
	ds_read_b64_tr_b16 v[94:95], v39
	ds_read_b64_tr_b16 v[98:99], v40
	s_waitcnt lgkmcnt(8)
	v_mfma_f32_16x16x32_bf16 v[228:231], v[100:103], v[184:187], v[228:231]
	v_mfma_f32_16x16x32_bf16 v[232:235], v[104:107], v[184:187], v[232:235]
	v_mfma_f32_16x16x32_bf16 v[236:239], v[108:111], v[184:187], v[236:239]
	v_mfma_f32_16x16x32_bf16 v[240:243], v[112:115], v[184:187], v[240:243]
	s_waitcnt lgkmcnt(0)
	v_mfma_f32_16x16x32_bf16 v[228:231], v[84:87], v[188:191], v[228:231]
	v_mfma_f32_16x16x32_bf16 v[232:235], v[88:91], v[188:191], v[232:235]
	v_mfma_f32_16x16x32_bf16 v[236:239], v[92:95], v[188:191], v[236:239]
	v_mfma_f32_16x16x32_bf16 v[240:243], v[96:99], v[188:191], v[240:243]
	v_mov_b32_e32 v0, v36
	v_mov_b32_e32 v1, v36
	s_nop 1
	v_permlane16_swap_b32_e32 v0, v1
	s_nop 1
	v_add_f32_e32 v36, v0, v1
	v_mov_b32_e32 v0, v36
	v_mov_b32_e32 v1, v36
	s_nop 1
	v_permlane32_swap_b32_e32 v0, v1
	s_nop 1
	v_add_f32_e32 v36, v0, v1
	s_cmp_lt_u32 s9, 16
	s_cbranch_scc0 .Latt_hasprev_42
	v_mov_b32_e32 v81, v223
	v_mov_b32_e32 v72, 0
	v_mov_b32_e32 v73, 0
	v_mov_b32_e32 v74, 0
	v_mov_b32_e32 v75, 0
	v_mov_b32_e32 v76, 0
	v_mov_b32_e32 v77, 0
	v_mov_b32_e32 v78, 0
	v_mov_b32_e32 v79, 0
	s_branch .Latt_noprev_43
.Latt_hasprev_42:
	v_permlane16_swap_b32_e32 v72, v74
	v_permlane16_swap_b32_e32 v73, v75
	v_permlane16_swap_b32_e32 v76, v78
	v_permlane16_swap_b32_e32 v77, v79
.Latt_noprev_43:
	v_max_f32_e32 v116, v81, v35
	v_sub_f32_e32 v117, v81, v116
	v_sub_f32_e32 v118, v35, v116
	v_exp_f32_e32 v117, v117
	v_exp_f32_e32 v118, v118
	s_lshl_b32 s5, s24, 7
	v_add_u32_e32 v83, s5, v17
	v_lshlrev_b32_e32 v83, s20, v83
	v_add_u32_e32 v83, s21, v83
	v_fma_f32 v119, v36, v118, v117
	v_rcp_f32_e32 v122, v119
	v_lshl_add_u32 v123, v83, 11, v19
	s_nop 0
	v_mul_f32_e32 v120, v117, v122
	v_mul_f32_e32 v121, v118, v122
	v_lshlrev_b32_e32 v124, 16, v72
	v_and_b32_e32 v125, 0xffff0000, v72
	v_lshlrev_b32_e32 v126, 16, v73
	v_and_b32_e32 v127, 0xffff0000, v73
	v_mul_f32_e32 v124, v120, v124
	v_mul_f32_e32 v125, v120, v125
	v_mul_f32_e32 v126, v120, v126
	v_mul_f32_e32 v127, v120, v127
	v_fma_f32 v124, v228, v121, v124
	v_fma_f32 v125, v229, v121, v125
	v_fma_f32 v126, v230, v121, v126
	v_fma_f32 v127, v231, v121, v127
	v_cvt_pk_bf16_f32 v84, v124, v125
	v_cvt_pk_bf16_f32 v85, v126, v127
	v_lshlrev_b32_e32 v124, 16, v74
	v_and_b32_e32 v125, 0xffff0000, v74
	v_lshlrev_b32_e32 v126, 16, v75
	v_and_b32_e32 v127, 0xffff0000, v75
	v_mul_f32_e32 v124, v120, v124
	v_mul_f32_e32 v125, v120, v125
	v_mul_f32_e32 v126, v120, v126
	v_mul_f32_e32 v127, v120, v127
	v_fma_f32 v124, v232, v121, v124
	v_fma_f32 v125, v233, v121, v125
	v_fma_f32 v126, v234, v121, v126
	v_fma_f32 v127, v235, v121, v127
	v_cvt_pk_bf16_f32 v86, v124, v125
	v_cvt_pk_bf16_f32 v87, v126, v127
	v_lshlrev_b32_e32 v124, 16, v76
	v_and_b32_e32 v125, 0xffff0000, v76
	v_lshlrev_b32_e32 v126, 16, v77
	v_and_b32_e32 v127, 0xffff0000, v77
	v_mul_f32_e32 v124, v120, v124
	v_mul_f32_e32 v125, v120, v125
	v_mul_f32_e32 v126, v120, v126
	v_mul_f32_e32 v127, v120, v127
	v_fma_f32 v124, v236, v121, v124
	v_fma_f32 v125, v237, v121, v125
	v_fma_f32 v126, v238, v121, v126
	v_fma_f32 v127, v239, v121, v127
	v_cvt_pk_bf16_f32 v88, v124, v125
	v_cvt_pk_bf16_f32 v89, v126, v127
	v_lshlrev_b32_e32 v124, 16, v78
	v_and_b32_e32 v125, 0xffff0000, v78
	v_lshlrev_b32_e32 v126, 16, v79
	v_and_b32_e32 v127, 0xffff0000, v79
	v_mul_f32_e32 v124, v120, v124
	v_mul_f32_e32 v125, v120, v125
	v_mul_f32_e32 v126, v120, v126
	v_mul_f32_e32 v127, v120, v127
	v_fma_f32 v124, v240, v121, v124
	v_fma_f32 v125, v241, v121, v125
	v_fma_f32 v126, v242, v121, v126
	v_fma_f32 v127, v243, v121, v127
	v_cvt_pk_bf16_f32 v90, v124, v125
	v_cvt_pk_bf16_f32 v91, v126, v127
	s_nop 1
	v_permlane16_swap_b32_e32 v84, v86
	v_permlane16_swap_b32_e32 v85, v87
	v_permlane16_swap_b32_e32 v88, v90
	v_permlane16_swap_b32_e32 v89, v91
	global_store_dwordx4 v123, v[84:87], s[42:43] offset:0
	global_store_dwordx4 v123, v[88:91], s[42:43] offset:64
	v_log_f32_e32 v130, v119
	v_lshlrev_b32_e32 v131, 2, v83
	s_nop 0
	v_add_f32_e32 v130, v116, v130
	s_mov_b64 exec, 0xffff
	global_store_dword v131, v130, s[44:45]
	s_mov_b64 exec, -1
	s_cmp_lt_u32 s4, 16
	s_cbranch_scc1 .Latt_odummy_44
	v_lshl_add_u32 v1, v82, 11, v19
	global_load_dwordx4 v[72:75], v1, s[42:43] offset:0
	global_load_dwordx4 v[76:79], v1, s[42:43] offset:64
	v_lshlrev_b32_e32 v0, 2, v82
	global_load_dword v81, v0, s[44:45]
	s_branch .Latt_odone_45
